# up-GEMM epilogue rewritten by hand: A rows staged permuted (lane holds 4 consecutive tokens) so the causal conv needs 2 lane shifts per channel instead of 8; packed silu; 16-byte act stores. Same f32
# speedup vs baseline: 1.0224x; 1.0224x over previous
; #define PG8_STAGE(bufoff, gbase, voff) do { _Pragma("unroll") for (int _i = 0; _i < 2; ++_i) \
;         __builtin_amdgcn_global_load_lds((const unsigned*)((const char*)(gbase) + (voff)[_i]), (PG8_LAS unsigned*)(lds + (bufoff) + ldsw + _i * 8192), 16, 0, 0); } while (0)
; #define PG8_WAIT_V(n) asm volatile("s_waitcnt vmcnt(" #n ")" ::: "memory")
; #define PG8_BAR __builtin_amdgcn_s_barrier()
; template <class Epi, class Sched, bool ALIGN_EPI = false, bool SP2 = false>
; __device__ __forceinline__ void gemm_phase(PG8_LAS unsigned char* lds, const Gemm g, const Sched& S, const Epi& E, int tid_in) {
;     ...
;     const int tid = tid_o, wid = __builtin_amdgcn_readfirstlane(tid >> 6), lane = tid & 63, wr = wid >> 2, wc = wid & 3, fr = lane & 15, fq = lane >> 4;
;     const int K = g.K, nt = K / BK;
;     unsigned voffA[2], voffB[2];
; #pragma unroll
;     for (int i = 0; i < 2; ++i) { int R, C; stage_rc(tid * 16 + i * 8192, R, C); const int Rb = Epi::PERM ? ((R & ~31) + perm32(R & 31)) : R;
;         voffA[i] = (unsigned)(R * K + C) * 2u; voffB[i] = (unsigned)(Rb * K + C) * 2u; }
;     const size_t kstep = (size_t)(BK * 2);
;     const size_t hstep = (size_t)HALF * K * 2;
;     const size_t tstep = 2 * hstep;
;     const unsigned ldsw = (unsigned)wid * 1024u;
;     const int aoff = lds_byte(wr * 64 + fr, fq * 8), boff = lds_byte(wc * 32 + fr, fq * 8);
;     ...
;     Unit cur, nxt; int ui = 0;
;     if (!S.next(0, cur)) return;
;     f32x4 acc[2][2][4][2];
; #pragma unroll
;     for (int a = 0; a < 2; ++a)
; #pragma unroll
;         for (int b = 0; b < 2; ++b)
; #pragma unroll
;             for (int m = 0; m < 4; ++m)
; #pragma unroll
;                 for (int n = 0; n < 2; ++n) acc[a][b][m][n] = (f32x4){0.f, 0.f, 0.f, 0.f};
;     bf16x8 At[4][2], B0[2][2], B1[2][2];
;     const char* cA = (const char*)g.A + (size_t)cur.pm * tstep; const char* cB = (const char*)g.Bt + (size_t)cur.pn * tstep;
;     S.a_ready(cur);
;     if constexpr (SP2) {
;         PG8_STAGE(PG8_SB(0, 0), cB, voffB); PG8_STAGE(PG8_SB(0, 1), cB + hstep, voffB); PG8_STAGE(PG8_SA(0, 0), cA, voffA); PG8_STAGE(PG8_SA(0, 1), cA + hstep, voffA);
;         if (wr == 1) PG8_BAR;
;         PG8_WAIT_V(2); PG8_BAR;
;         PG8_STAGE(PG8_SB(1, 0), cB + kstep, voffB); PG8_STAGE(PG8_SA(1, 0), cA + kstep, voffA); PG8_STAGE(PG8_SB(1, 1), cB + hstep + kstep, voffB);
;         PG8_WAIT_V(6); PG8_BAR;
.LBB0_707:
	s_mul_hi_u32 s49, s44, 0x8400
	s_mul_i32 s48, s44, 0x8400
	s_mul_hi_u32 s47, s44, 0x2c00
	s_andn2_b64 vcc, exec, s[10:11]
	s_mul_i32 s46, s44, 0x2c00
	s_cbranch_vccnz .LBB0_753
	v_ashrrev_i32_e32 v1, 31, v14
	v_lshrrev_b32_e32 v1, 26, v1
	v_add_u32_e32 v1, v14, v1
	v_ashrrev_i32_e32 v8, 6, v1
	v_bfe_i32 v1, v14, 27, 1
	v_lshlrev_b32_e32 v0, 4, v14
	v_lshrrev_b32_e32 v1, 22, v1
	v_add_u32_e32 v1, v0, v1
	v_and_b32_e32 v1, 0xfffffc00, v1
	v_sub_u32_e32 v1, v0, v1
	v_lshrrev_b32_e32 v2, 4, v1
	v_bitop3_b32 v1, v2, v1, 32 bitop3:0x6c
	v_ashrrev_i32_e32 v3, 31, v1
	v_lshrrev_b32_e32 v3, 26, v3
	v_add_u32_e32 v3, v1, v3
	v_lshlrev_b32_e32 v2, 3, v8
	v_ashrrev_i32_e32 v9, 6, v3
	v_and_b32_e32 v3, 0xc0, v3
	v_and_b32_e32 v2, -16, v2
	v_sub_u32_e32 v1, v1, v3
	v_add_u32_e32 v2, v9, v2
	v_ashrrev_i16_sdwa v1, v249, sext(v1) dst_sel:DWORD dst_unused:UNUSED_PAD src0_sel:DWORD src1_sel:BYTE_0
	v_lshlrev_b32_e32 v4, 5, v8
	v_bfe_i32 v10, v1, 0, 16
	v_lshlrev_b32_e32 v1, 1, v2
	v_lshrrev_b32_e32 v3, 2, v2
	v_and_b32_e32 v5, 3, v9
	s_mov_b32 s9, 0xfffe0
	v_and_b32_e32 v4, 32, v4
	v_and_b32_e32 v1, 24, v1
	v_and_b32_e32 v3, 4, v3
	v_and_or_b32 v5, v2, s9, v5
	v_or3_b32 v1, v5, v3, v1
	v_add_lshl_u32 v3, v4, v10, 1
	v_add_u32_e32 v0, 0x2000, v0
	v_lshl_add_u32 v172, v1, 12, v3
	v_ashrrev_i32_e32 v1, 31, v0
	v_lshrrev_b32_e32 v1, 22, v1
	v_add_u32_e32 v1, v0, v1
	v_ashrrev_i32_e32 v11, 10, v1
	v_mul_i32_i24_e32 v1, 0x400, v11
	v_sub_u32_e32 v0, v0, v1
	v_lshrrev_b32_e32 v1, 4, v0
	v_bitop3_b32 v0, v1, v0, 32 bitop3:0x6c
	v_lshl_add_u32 v170, v2, 12, v3
	v_ashrrev_i32_e32 v2, 31, v0
	v_lshrrev_b32_e32 v2, 26, v2
	s_waitcnt lgkmcnt(0)
	s_add_u32 s45, s58, 0x32800000
	v_lshlrev_b32_e32 v1, 3, v11
	v_add_u32_e32 v2, v0, v2
	s_addc_u32 s82, s59, 0
	v_and_b32_e32 v1, -16, v1
	v_ashrrev_i32_e32 v12, 6, v2
	s_add_u32 s83, s58, 0x1d00000
	v_add_u32_e32 v1, v12, v1
	v_and_b32_e32 v4, 3, v12
	s_addc_u32 s84, s59, 0
	v_and_b32_e32 v2, 0xc0, v2
	v_and_or_b32 v4, v1, s9, v4
	s_ashr_i32 s26, s12, 6
	s_ashr_i32 s9, s8, 31
	s_ashr_i32 s77, s76, 31
	s_ashr_i32 s16, s12, 8
	v_sub_u32_e32 v0, v0, v2
	s_lshl_b32 s85, s26, 10
	s_lshl_b64 s[34:35], s[8:9], 20
	s_lshl_b64 s[10:11], s[76:77], 20
	v_ashrrev_i16_sdwa v0, v249, sext(v0) dst_sel:DWORD dst_unused:UNUSED_PAD src0_sel:DWORD src1_sel:BYTE_0
	s_add_u32 s10, s83, s10
	v_lshlrev_b32_e32 v3, 5, v11
	v_bfe_i32 v13, v0, 0, 16
	v_lshlrev_b32_e32 v0, 1, v1
	v_lshrrev_b32_e32 v2, 2, v1
	s_addc_u32 s11, s84, s11
	s_add_i32 s27, s85, 0
	v_and_b32_e32 v3, 32, v3
	v_and_b32_e32 v0, 24, v0
	v_and_b32_e32 v2, 4, v2
	s_add_i32 m0, s27, 0x10000
	v_or3_b32 v0, v4, v2, v0
	v_add_lshl_u32 v2, v3, v13, 1
	global_load_lds_dwordx4 v172, s[10:11]
	s_add_i32 m0, s27, 0x12000
	v_lshl_add_u32 v176, v0, 12, v2
	s_add_u32 s38, s10, 0x80000
	global_load_lds_dwordx4 v176, s[10:11]
	s_addc_u32 s39, s11, 0
	s_add_i32 m0, s27, 0x14000
	v_lshl_add_u32 v174, v1, 12, v2
	v_lshrrev_b32_e32 v243, 2, v250
	v_mul_u32_u24_e32 v243, 3, v243
	s_lshr_b32 s98, s3, 1
	s_mul_i32 s98, s98, 15
	v_subrev_u32_e32 v243, s98, v243
	v_lshlrev_b32_e32 v243, 12, v243
	v_add_u32_e32 v170, v243, v170
	v_add_u32_e32 v174, v243, v174
	global_load_lds_dwordx4 v172, s[38:39]
	s_add_i32 m0, s27, 0x16000
	s_add_u32 s78, s45, s34
	s_addc_u32 s79, s82, s35
	s_add_i32 s87, s27, 0x2000
	global_load_lds_dwordx4 v176, s[38:39]
	s_mov_b32 m0, s27
	s_add_u32 s34, s78, 0x80000
	global_load_lds_dwordx4 v170, s[78:79]
	s_mov_b32 m0, s87
	s_addc_u32 s35, s79, 0
	s_add_i32 s38, s27, 0x4000
	global_load_lds_dwordx4 v174, s[78:79]
	s_mov_b32 m0, s38
	s_add_i32 s39, s27, 0x6000
	global_load_lds_dwordx4 v170, s[34:35]
	s_mov_b32 m0, s39
	v_mov_b32_e32 v173, v20
	global_load_lds_dwordx4 v174, s[34:35]
	v_mov_b32_e32 v177, v20
	v_mov_b32_e32 v171, v20
	v_mov_b32_e32 v175, v20
	s_cmp_eq_u32 s16, 1
	v_lshl_add_u64 v[6:7], s[10:11], 0, v[172:173]
	v_lshl_add_u64 v[4:5], s[10:11], 0, v[176:177]
	v_lshl_add_u64 v[0:1], s[78:79], 0, v[170:171]
	s_cselect_b64 s[50:51], -1, 0
	s_cmp_lg_u32 s16, 1
	v_lshl_add_u64 v[2:3], s[78:79], 0, v[174:175]
	s_cbranch_scc1 .LBB0_710
	s_barrier
.LBB0_710:
	s_load_dwordx2 s[24:25], s[0:1], 0x90
	v_and_b32_e32 v15, 48, v14
	s_waitcnt vmcnt(0)
	v_lshlrev_b32_e32 v16, 6, v14
	v_lshlrev_b32_e32 v14, 2, v14
	v_and_b32_e32 v14, 32, v14
	s_waitcnt lgkmcnt(0)
	s_add_i32 s14, s14, s24
	s_add_u32 s52, s58, 0x1c800000
	s_addc_u32 s53, s59, 0
	s_lshl_b64 s[34:35], s[48:49], 2
	s_add_u32 s54, s4, s34
	s_addc_u32 s55, s5, s35
	s_lshl_b64 s[4:5], s[46:47], 2
	s_add_u32 s56, s6, s4
	s_addc_u32 s57, s7, s5
	s_add_u32 s15, s58, 0x48800000
	s_addc_u32 s95, s59, 0
	s_add_u32 s58, s58, 0x4a820000
	s_movk_i32 s5, 0x3c0
	s_addc_u32 s59, s59, 0
	s_lshl_b32 s4, s16, 13
	v_and_or_b32 v15, v16, s5, v15
	v_bitop3_b32 v16, v15, s4, v14 bitop3:0xde
	s_lshl_b32 s4, s26, 5
	s_and_b32 s97, s4, 0x60
	s_add_i32 m0, s27, 0x18000
	v_lshl_add_u64 v[6:7], v[6:7], 0, s[22:23]
	s_lshl_b32 s96, s16, 6
	s_lshl_b32 s4, s97, 7
	s_waitcnt vmcnt(2)
	s_barrier
	global_load_lds_dwordx4 v[6:7], off
	v_lshl_add_u64 v[4:5], v[4:5], 0, s[22:23]
	s_add_i32 m0, s27, 0x1a000
	s_add_i32 s26, s27, 0x8000
	s_add_i32 s90, s27, 0xa000
	v_bitop3_b32 v21, s4, v15, v14 bitop3:0xf6
	global_load_lds_dwordx4 v[4:5], off
	v_lshl_add_u64 v[0:1], v[0:1], 0, s[22:23]
	s_mov_b32 m0, s26
	s_add_u32 s4, s10, 0x80080
	global_load_lds_dwordx4 v[0:1], off
	v_lshl_add_u64 v[0:1], v[2:3], 0, s[22:23]
	s_mov_b32 m0, s90
	s_addc_u32 s5, s11, 0
	global_load_lds_dwordx4 v[0:1], off
	s_add_i32 m0, s27, 0x1c000
	v_lshl_add_u64 v[0:1], s[4:5], 0, v[172:173]
	global_load_lds_dwordx4 v[0:1], off
	v_lshl_add_u64 v[0:1], s[4:5], 0, v[176:177]
	s_add_i32 m0, s27, 0x1e000
	s_cmpk_lt_u32 s12, 0x100
	global_load_lds_dwordx4 v[0:1], off
	v_lshlrev_b32_e32 v0, 15, v8
	s_cselect_b64 s[60:61], -1, 0
	s_lshl_b32 s43, s16, 1
	v_and_b32_e32 v0, 0xffff0000, v0
	s_add_i32 s43, s43, 0x3ffff2
	v_lshl_add_u32 v0, v9, 12, v0
	v_and_b32_e32 v1, 1, v8
	s_cmp_gt_i32 s16, 0
	v_lshl_or_b32 v0, v1, 6, v0
	s_cselect_b64 s[62:63], -1, 0
	s_lshl_b32 s4, s16, 11
	s_add_i32 s5, s16, 2
	v_lshl_add_u32 v178, v10, 1, v0
	v_add_u32_e32 v178, v243, v178
	v_lshlrev_b32_e32 v0, 15, v11
	s_cmp_gt_i32 s16, -2
	v_and_b32_e32 v0, 0xffff0000, v0
	s_waitcnt vmcnt(6)
	s_cselect_b64 s[64:65], -1, 0
	s_lshl_b32 s6, s5, 11
	v_lshl_add_u32 v0, v12, 12, v0
	v_and_b32_e32 v1, 1, v11
	s_cmp_eq_u32 s5, 0
	v_lshl_or_b32 v0, v1, 6, v0
	s_mov_b32 s12, 0
	s_cselect_b64 s[66:67], -1, 0
	s_ashr_i32 s34, s14, 31
	s_ashr_i32 s35, s18, 31
	s_add_i32 s16, s36, s4
	s_add_i32 s37, s36, s6
	v_mov_b32_e32 v179, v20
	v_lshl_add_u32 v180, v13, 1, v0
	v_add_u32_e32 v180, v243, v180
	v_mov_b32_e32 v181, v20
	v_add_u32_e32 v254, 0, v16
	s_barrier
	s_branch .LBB0_713

; #define PG8_LAS __attribute__((address_space(3)))
;     __device__ __forceinline__ void operator()(const f32x4 (&acc_)[2][2][4][2], const Unit& u, int wr, int wc, int fr_, int fq_) const {
;         unsigned lz_ = 0u; asm volatile("" : "+v"(lz_)); const int ln_ = __builtin_amdgcn_mbcnt_hi(~0u, __builtin_amdgcn_mbcnt_lo(~0u, lz_)); const int fr = ln_ & 15, fq = ln_ >> 4; (void)fr_; (void)fq_;
;         const int chl = wc * 32 + 8 * fq, ch0 = u.pn * 128 + chl;
;         f32x4 (&acc)[2][2][4][2] = const_cast<f32x4 (&)[2][2][4][2]>(acc_);
;         { float scs[2][4]; row_rstd8(scs, rs, u.pm * BM + wr * 64 + fr, fq);
; #pragma unroll
;           for (int ai = 0; ai < 2; ++ai)
; #pragma unroll
;               for (int m = 0; m < 4; ++m)
; #pragma unroll
;                   for (int bj = 0; bj < 2; ++bj)
; #pragma unroll
;                       for (int n = 0; n < 2; ++n) acc[ai][bj][m][n] = acc[ai][bj][m][n] * scs[ai][m]; }
;         if (fr >= 14) {
; #pragma unroll
;             for (int ai = 0; ai < 2; ++ai)
; #pragma unroll
;                 for (int bj = 0; bj < 2; ++bj)
; #pragma unroll
;                     for (int n = 0; n < 2; ++n) *(PG8_LAS f32x4*)(xch + ((2 * ai + wr) * 2 + (fr - 14)) * 256 + bj * 128 + chl + 4 * n) = acc[ai][bj][3][n];
;     ...
;             f32x4 wgt[3][2], bia[2];
; #pragma unroll
;             for (int bj = 0; bj < 2; ++bj) { bia[bj] = *(const f32x4*)(cb + bj * FF + ch0 + 4 * n);
; #pragma unroll
;                 for (int i = 0; i < 3; ++i) wgt[i][bj] = *(const f32x4*)(cw + i * UWc + bj * FF + ch0 + 4 * n); }
.LBB0_719:
	s_mov_b32 s98, s8
	s_mov_b32 s99, s76
	s_lshr_b32 s100, s3, 2
	s_and_b32 s101, s3, 3
	v_and_b32_e32 v168, 15, v250
	v_lshrrev_b32_e32 v139, 4, v250
	s_lshl_b32 s101, s101, 7
	v_lshl_add_u32 v138, v139, 5, s101
	s_lshl_b32 s6, s98, 10
	s_lshl_b32 s7, s100, 8
	s_add_u32 s6, s6, s7
	s_add_u32 s24, s58, s6
	s_addc_u32 s25, s59, 0
	v_lshlrev_b32_e32 v139, 4, v168
	global_load_dwordx4 v[130:133], v139, s[24:25]
	global_load_dwordx4 v[134:137], v139, s[24:25] offset:512
	s_lshl_b32 s6, s99, 9
	s_add_u32 s24, s54, s6
	s_addc_u32 s25, s55, 0
	s_add_u32 s10, s56, s6
	s_addc_u32 s11, s57, 0
	global_load_dwordx4 v[144:147], v138, s[24:25]
	global_load_dwordx4 v[190:193], v138, s[24:25] offset:16
	global_load_dwordx4 v[182:185], v138, s[10:11]
	global_load_dwordx4 v[218:221], v138, s[10:11] offset:16
	v_add_u32_e32 v139, 0x5800, v138
	global_load_dwordx4 v[148:151], v139, s[24:25]
	global_load_dwordx4 v[194:197], v139, s[24:25] offset:16
	global_load_dwordx4 v[186:189], v139, s[10:11]
	global_load_dwordx4 v[222:225], v139, s[10:11] offset:16
	v_add_u32_e32 v139, 0xb000, v138
	global_load_dwordx4 v[152:155], v139, s[24:25]
	global_load_dwordx4 v[198:201], v139, s[24:25] offset:16
	v_add_u32_e32 v139, 0x10800, v138
	global_load_dwordx4 v[156:159], v139, s[24:25]
	global_load_dwordx4 v[202:205], v139, s[24:25] offset:16
	v_add_u32_e32 v139, 0x16000, v138
	global_load_dwordx4 v[160:163], v139, s[24:25]
	global_load_dwordx4 v[206:209], v139, s[24:25] offset:16
	v_add_u32_e32 v139, 0x1b800, v138
	global_load_dwordx4 v[164:167], v139, s[24:25]
	global_load_dwordx4 v[210:213], v139, s[24:25] offset:16
	s_waitcnt vmcnt(16)
	v_pk_mul_f32 v[126:127], v[126:127], v[130:131] op_sel_hi:[1,0]
	v_pk_mul_f32 v[128:129], v[128:129], v[130:131] op_sel_hi:[1,0]
	v_pk_mul_f32 v[82:83], v[82:83], v[130:131] op_sel_hi:[1,0]
	v_pk_mul_f32 v[84:85], v[84:85], v[130:131] op_sel_hi:[1,0]
	v_pk_mul_f32 v[122:123], v[122:123], v[130:131] op_sel_hi:[1,0]
	v_pk_mul_f32 v[124:125], v[124:125], v[130:131] op_sel_hi:[1,0]
	v_pk_mul_f32 v[78:79], v[78:79], v[130:131] op_sel_hi:[1,0]
	v_pk_mul_f32 v[80:81], v[80:81], v[130:131] op_sel_hi:[1,0]
	v_pk_mul_f32 v[110:111], v[110:111], v[130:131] op_sel:[0,1] op_sel_hi:[1,1]
	v_pk_mul_f32 v[112:113], v[112:113], v[130:131] op_sel:[0,1] op_sel_hi:[1,1]
	v_pk_mul_f32 v[46:47], v[46:47], v[130:131] op_sel:[0,1] op_sel_hi:[1,1]
	v_pk_mul_f32 v[48:49], v[48:49], v[130:131] op_sel:[0,1] op_sel_hi:[1,1]
	v_pk_mul_f32 v[102:103], v[102:103], v[130:131] op_sel:[0,1] op_sel_hi:[1,1]
	v_pk_mul_f32 v[104:105], v[104:105], v[130:131] op_sel:[0,1] op_sel_hi:[1,1]
	v_pk_mul_f32 v[38:39], v[38:39], v[130:131] op_sel:[0,1] op_sel_hi:[1,1]
	v_pk_mul_f32 v[40:41], v[40:41], v[130:131] op_sel:[0,1] op_sel_hi:[1,1]
	v_pk_mul_f32 v[106:107], v[106:107], v[132:133] op_sel_hi:[1,0]
	v_pk_mul_f32 v[108:109], v[108:109], v[132:133] op_sel_hi:[1,0]
	v_pk_mul_f32 v[42:43], v[42:43], v[132:133] op_sel_hi:[1,0]
	v_pk_mul_f32 v[44:45], v[44:45], v[132:133] op_sel_hi:[1,0]
	v_pk_mul_f32 v[98:99], v[98:99], v[132:133] op_sel_hi:[1,0]
	v_pk_mul_f32 v[100:101], v[100:101], v[132:133] op_sel_hi:[1,0]
	v_pk_mul_f32 v[34:35], v[34:35], v[132:133] op_sel_hi:[1,0]
	v_pk_mul_f32 v[36:37], v[36:37], v[132:133] op_sel_hi:[1,0]
	v_pk_mul_f32 v[114:115], v[114:115], v[132:133] op_sel:[0,1] op_sel_hi:[1,1]
	v_pk_mul_f32 v[116:117], v[116:117], v[132:133] op_sel:[0,1] op_sel_hi:[1,1]
	v_pk_mul_f32 v[50:51], v[50:51], v[132:133] op_sel:[0,1] op_sel_hi:[1,1]
	v_pk_mul_f32 v[52:53], v[52:53], v[132:133] op_sel:[0,1] op_sel_hi:[1,1]
	v_pk_mul_f32 v[118:119], v[118:119], v[132:133] op_sel:[0,1] op_sel_hi:[1,1]
	v_pk_mul_f32 v[120:121], v[120:121], v[132:133] op_sel:[0,1] op_sel_hi:[1,1]
	v_pk_mul_f32 v[54:55], v[54:55], v[132:133] op_sel:[0,1] op_sel_hi:[1,1]
	v_pk_mul_f32 v[56:57], v[56:57], v[132:133] op_sel:[0,1] op_sel_hi:[1,1]
	v_pk_mul_f32 v[86:87], v[86:87], v[134:135] op_sel_hi:[1,0]
	v_pk_mul_f32 v[88:89], v[88:89], v[134:135] op_sel_hi:[1,0]
	v_pk_mul_f32 v[22:23], v[22:23], v[134:135] op_sel_hi:[1,0]
	v_pk_mul_f32 v[24:25], v[24:25], v[134:135] op_sel_hi:[1,0]
	v_pk_mul_f32 v[74:75], v[74:75], v[134:135] op_sel_hi:[1,0]
	v_pk_mul_f32 v[76:77], v[76:77], v[134:135] op_sel_hi:[1,0]
	v_pk_mul_f32 v[16:17], v[16:17], v[134:135] op_sel_hi:[1,0]
	v_pk_mul_f32 v[18:19], v[18:19], v[134:135] op_sel_hi:[1,0]
	v_pk_mul_f32 v[70:71], v[70:71], v[134:135] op_sel:[0,1] op_sel_hi:[1,1]
	v_pk_mul_f32 v[72:73], v[72:73], v[134:135] op_sel:[0,1] op_sel_hi:[1,1]
	v_pk_mul_f32 v[12:13], v[12:13], v[134:135] op_sel:[0,1] op_sel_hi:[1,1]
	v_pk_mul_f32 v[14:15], v[14:15], v[134:135] op_sel:[0,1] op_sel_hi:[1,1]
	v_pk_mul_f32 v[62:63], v[62:63], v[134:135] op_sel:[0,1] op_sel_hi:[1,1]
	v_pk_mul_f32 v[64:65], v[64:65], v[134:135] op_sel:[0,1] op_sel_hi:[1,1]
	v_pk_mul_f32 v[4:5], v[4:5], v[134:135] op_sel:[0,1] op_sel_hi:[1,1]
	v_pk_mul_f32 v[6:7], v[6:7], v[134:135] op_sel:[0,1] op_sel_hi:[1,1]
	v_pk_mul_f32 v[66:67], v[66:67], v[136:137] op_sel_hi:[1,0]
	v_pk_mul_f32 v[68:69], v[68:69], v[136:137] op_sel_hi:[1,0]
	v_pk_mul_f32 v[8:9], v[8:9], v[136:137] op_sel_hi:[1,0]
	v_pk_mul_f32 v[10:11], v[10:11], v[136:137] op_sel_hi:[1,0]
	v_pk_mul_f32 v[58:59], v[58:59], v[136:137] op_sel_hi:[1,0]
	v_pk_mul_f32 v[60:61], v[60:61], v[136:137] op_sel_hi:[1,0]
	v_pk_mul_f32 v[0:1], v[0:1], v[136:137] op_sel_hi:[1,0]
	v_pk_mul_f32 v[2:3], v[2:3], v[136:137] op_sel_hi:[1,0]
	v_pk_mul_f32 v[90:91], v[90:91], v[136:137] op_sel:[0,1] op_sel_hi:[1,1]
	v_pk_mul_f32 v[92:93], v[92:93], v[136:137] op_sel:[0,1] op_sel_hi:[1,1]
	v_pk_mul_f32 v[26:27], v[26:27], v[136:137] op_sel:[0,1] op_sel_hi:[1,1]
	v_pk_mul_f32 v[28:29], v[28:29], v[136:137] op_sel:[0,1] op_sel_hi:[1,1]
	v_pk_mul_f32 v[94:95], v[94:95], v[136:137] op_sel:[0,1] op_sel_hi:[1,1]
	v_pk_mul_f32 v[96:97], v[96:97], v[136:137] op_sel:[0,1] op_sel_hi:[1,1]
	v_pk_mul_f32 v[30:31], v[30:31], v[136:137] op_sel:[0,1] op_sel_hi:[1,1]
	v_pk_mul_f32 v[32:33], v[32:33], v[136:137] op_sel:[0,1] op_sel_hi:[1,1]
	v_cmp_eq_u32_e64 s[76:77], 15, v168
	s_lshl_b32 s6, s100, 11
	s_add_i32 s6, s6, 0x20040
	v_add_u32_e32 v142, s6, v138
	v_add_u32_e32 v143, 0xfffff800, v142
	s_mul_i32 s6, s98, 0x2c000
	s_lshl_b32 s7, s99, 10
	s_add_u32 s6, s6, s7
	s_add_u32 s10, s15, s6
	s_addc_u32 s11, s95, 0
	s_and_saveexec_b64 s[78:79], s[76:77]
	ds_write_b128 v142, v[106:109] offset:0
	ds_write_b128 v142, v[114:117] offset:1024
	ds_write_b128 v142, v[42:45] offset:16
	ds_write_b128 v142, v[50:53] offset:1040
	ds_write_b128 v142, v[98:101] offset:512
	ds_write_b128 v142, v[118:121] offset:1536
	ds_write_b128 v142, v[34:37] offset:528
	ds_write_b128 v142, v[54:57] offset:1552
	ds_write_b128 v142, v[66:69] offset:4096
	ds_write_b128 v142, v[90:93] offset:5120
	ds_write_b128 v142, v[8:11] offset:4112
	ds_write_b128 v142, v[26:29] offset:5136
	ds_write_b128 v142, v[58:61] offset:4608
	ds_write_b128 v142, v[94:97] offset:5632
	ds_write_b128 v142, v[0:3] offset:4624
	ds_write_b128 v142, v[30:33] offset:5648
	s_cmp_lg_u32 s100, 1
	s_cbranch_scc1 .Lue_h1
; #define PG8_LAS __attribute__((address_space(3)))
;     __device__ __forceinline__ void operator()(const f32x4 (&acc_)[2][2][4][2], const Unit& u, int wr, int wc, int fr_, int fq_) const {
;     ...
;         { float* uht = uh + (size_t)u.pm * 4 * UWc + u.pn * 256 + chl;
;           if (wr == 0 && fr < 2) {
; #pragma unroll
;               for (int bj = 0; bj < 2; ++bj)
; #pragma unroll
;                   for (int n = 0; n < 2; ++n) *(f32x4*)(uht + fr * UWc + bj * 128 + 4 * n) = acc[0][bj][0][n]; }
;           if (wr == 1 && fr >= 14) {
; #pragma unroll
;               for (int bj = 0; bj < 2; ++bj)
; #pragma unroll
;                   for (int n = 0; n < 2; ++n) *(f32x4*)(uht + (fr - 12) * UWc + bj * 128 + 4 * n) = acc[1][bj][3][n]; } }
;         asm volatile("s_waitcnt lgkmcnt(0)" ::: "memory"); __builtin_amdgcn_s_barrier(); asm volatile("" ::: "memory");
;         const bool seq0 = ((u.pm * BM) & 4095) == 0;
; #pragma unroll
;         for (int n = 0; n < 2; ++n) {
;             f32x4 wgt[3][2], bia[2];
; #pragma unroll
;             for (int bj = 0; bj < 2; ++bj) { bia[bj] = *(const f32x4*)(cb + bj * FF + ch0 + 4 * n);
; #pragma unroll
;                 for (int i = 0; i < 3; ++i) wgt[i][bj] = *(const f32x4*)(cw + i * UWc + bj * FF + ch0 + 4 * n); }
; #pragma unroll
;             for (int ai = 0; ai < 2; ++ai) {
;                 const int bi = 2 * ai + wr;
;                 f32x4 prev[2];
; #pragma unroll
;                 for (int bj = 0; bj < 2; ++bj) { const f32x4 v = *(const PG8_LAS f32x4*)(xch + ((bi > 0 ? bi - 1 : 0) * 2 + (fr & 1)) * 256 + bj * 128 + chl + 4 * n);
;                     prev[bj] = bi > 0 ? v : (f32x4){0.f, 0.f, 0.f, 0.f}; }
	s_add_u32 s6, s10, 0x16000
	s_addc_u32 s7, s11, 0
	global_store_dwordx4 v138, v[66:69], s[6:7] offset:0
	global_store_dwordx4 v138, v[8:11], s[6:7] offset:16
	global_store_dwordx4 v138, v[58:61], s[6:7] offset:512
	global_store_dwordx4 v138, v[0:3], s[6:7] offset:528
	s_add_u32 s6, s6, 0xb000
	s_addc_u32 s7, s7, 0
	global_store_dwordx4 v138, v[90:93], s[6:7] offset:0
	global_store_dwordx4 v138, v[26:29], s[6:7] offset:16
	global_store_dwordx4 v138, v[94:97], s[6:7] offset:512
	global_store_dwordx4 v138, v[30:33], s[6:7] offset:528
.Lue_h1:
	s_mov_b64 exec, s[78:79]
	v_cmp_eq_u32_e64 s[76:77], 0, v168
	s_cmp_lg_u32 s100, 0
	s_cbranch_scc1 .Lue_h2
	s_and_saveexec_b64 s[78:79], s[76:77]
	global_store_dwordx4 v138, v[126:129], s[10:11] offset:0
	global_store_dwordx4 v138, v[82:85], s[10:11] offset:16
	global_store_dwordx4 v138, v[122:125], s[10:11] offset:512
	global_store_dwordx4 v138, v[78:81], s[10:11] offset:528
	s_add_u32 s6, s10, 0xb000
	s_addc_u32 s7, s11, 0
	global_store_dwordx4 v138, v[110:113], s[6:7] offset:0
	global_store_dwordx4 v138, v[46:49], s[6:7] offset:16
	global_store_dwordx4 v138, v[102:105], s[6:7] offset:512
	global_store_dwordx4 v138, v[38:41], s[6:7] offset:528
	s_mov_b64 exec, s[78:79]
.Lue_h2:
	s_and_b32 s6, s98, 15
	s_cmp_eq_u32 s6, 0
	s_cselect_b64 s[76:77], 0, s[76:77]
	s_cmp_lg_u32 s100, 0
	s_cselect_b64 s[76:77], 0, s[76:77]
	s_waitcnt lgkmcnt(0)
	s_barrier
	s_mov_b32 s80, 0xbfb8aa3b
	s_mov_b32 s81, 0xbfb8aa3b
	s_mov_b32 s24, 1.0
	s_mov_b32 s25, 1.0
	s_mul_i32 s6, s98, 0x2c0000
	s_lshl_b32 s7, s99, 8
	s_add_u32 s6, s6, s7
	s_add_u32 s8, s52, s6
	s_addc_u32 s9, s53, 0
	s_lshl_b32 s6, s100, 6
	v_lshl_add_u32 v140, v168, 2, s6
	v_mul_u32_u24_e32 v140, 0x2c00, v140
	v_lshrrev_b32_e32 v139, 1, v138
	v_add_u32_e32 v140, v140, v139
	s_waitcnt vmcnt(8)
	s_cmp_eq_u32 s100, 0
	s_cbranch_scc1 .Lue_z00
	ds_read_b128 v[226:229], v143 offset:0
	ds_read_b128 v[230:233], v143 offset:1024
	ds_read_b128 v[234:237], v143 offset:512
	ds_read_b128 v[238:241], v143 offset:1536
	s_branch .Lue_r00
.Lue_z00:
	v_mov_b32_e32 v226, 0
	v_mov_b32_e32 v227, 0
	v_mov_b32_e32 v228, 0
	v_mov_b32_e32 v229, 0
	v_mov_b32_e32 v230, 0
	v_mov_b32_e32 v231, 0
	v_mov_b32_e32 v232, 0
	v_mov_b32_e32 v233, 0
	v_mov_b32_e32 v234, 0
	v_mov_b32_e32 v235, 0
	v_mov_b32_e32 v236, 0
	v_mov_b32_e32 v237, 0
	v_mov_b32_e32 v238, 0
	v_mov_b32_e32 v239, 0
	v_mov_b32_e32 v240, 0
	v_mov_b32_e32 v241, 0
; #define PG8_LAS __attribute__((address_space(3)))
; __device__ __forceinline__ unsigned cvt_pk_bf16(float lo, float hi) { unsigned r; asm volatile("v_cvt_pk_bf16_f32 %0, %1, %2" : "=v"(r) : "v"(lo), "v"(hi)); return r; }
; __device__ __forceinline__ float dpp_ror1(float s) { return __int_as_float(__builtin_amdgcn_mov_dpp(__float_as_int(s), 0x121, 0xf, 0xf, false)); }
; __device__ __forceinline__ float dpp_ror2(float s) { return __int_as_float(__builtin_amdgcn_mov_dpp(__float_as_int(s), 0x122, 0xf, 0xf, false)); }
;     __device__ __forceinline__ void operator()(const f32x4 (&acc_)[2][2][4][2], const Unit& u, int wr, int wc, int fr_, int fq_) const {
;     ...
;             for (int ai = 0; ai < 2; ++ai) {
;                 const int bi = 2 * ai + wr;
;                 f32x4 prev[2];
; #pragma unroll
;                 for (int bj = 0; bj < 2; ++bj) { const f32x4 v = *(const PG8_LAS f32x4*)(xch + ((bi > 0 ? bi - 1 : 0) * 2 + (fr & 1)) * 256 + bj * 128 + chl + 4 * n);
;                     prev[bj] = bi > 0 ? v : (f32x4){0.f, 0.f, 0.f, 0.f}; }
; #pragma unroll
;                 for (int m = 0; m < 4; ++m) {
;                     float o[4];
; #pragma unroll
;                     for (int e = 0; e < 4; ++e) {
;                         const float gc = acc[ai][0][m][n][e], gp = prev[0][e]; const float g1 = dpp_shr1(dpp_ror1(gp), gc), g2 = dpp_shr2(dpp_ror2(gp), gc);
;                         const float uc = acc[ai][1][m][n][e], up = prev[1][e]; const float u1 = dpp_shr1(dpp_ror1(up), uc), u2 = dpp_shr2(dpp_ror2(up), uc);
;                         const float gv = bia[0][e] + wgt[0][0][e] * g2 + wgt[1][0][e] * g1 + wgt[2][0][e] * gc;
;                         const float uv = bia[1][e] + wgt[0][1][e] * u2 + wgt[1][1][e] * u1 + wgt[2][1][e] * uc;
;                         o[e] = gv * __builtin_amdgcn_rcpf(1.0f + __builtin_amdgcn_exp2f(-1.4426950408889634f * gv)) * uv; }
;                     prev[0] = acc[ai][0][m][n]; prev[1] = acc[ai][1][m][n];
;                     const int row = u.pm * BM + ai * HALF + wr * 64 + m * 16 + fr;
;                     if (!(bi == 0 && m == 0 && fr < 2 && !seq0)) { u32x2 w; w.x = cvt_pk_bf16(o[0], o[1]); w.y = cvt_pk_bf16(o[2], o[3]); *(u32x2*)(act + (size_t)row * FF + ch0 + 4 * n) = w; }
.Lue_r00:
	s_waitcnt lgkmcnt(0)
	v_mov_b32_dpp v230, v114 row_shr:1 row_mask:0xf bank_mask:0xf
	v_mov_b32_dpp v231, v115 row_shr:1 row_mask:0xf bank_mask:0xf
	v_mov_b32_dpp v232, v116 row_shr:1 row_mask:0xf bank_mask:0xf
	v_mov_b32_dpp v233, v117 row_shr:1 row_mask:0xf bank_mask:0xf
	v_mov_b32_dpp v238, v118 row_shr:1 row_mask:0xf bank_mask:0xf
	v_mov_b32_dpp v239, v119 row_shr:1 row_mask:0xf bank_mask:0xf
	v_mov_b32_dpp v240, v120 row_shr:1 row_mask:0xf bank_mask:0xf
	v_mov_b32_dpp v241, v121 row_shr:1 row_mask:0xf bank_mask:0xf
	v_mov_b32_dpp v226, v106 row_shr:1 row_mask:0xf bank_mask:0xf
	v_mov_b32_dpp v227, v107 row_shr:1 row_mask:0xf bank_mask:0xf
	v_mov_b32_dpp v228, v108 row_shr:1 row_mask:0xf bank_mask:0xf
	v_mov_b32_dpp v229, v109 row_shr:1 row_mask:0xf bank_mask:0xf
	v_mov_b32_dpp v234, v98 row_shr:1 row_mask:0xf bank_mask:0xf
	v_mov_b32_dpp v235, v99 row_shr:1 row_mask:0xf bank_mask:0xf
	v_mov_b32_dpp v236, v100 row_shr:1 row_mask:0xf bank_mask:0xf
	v_mov_b32_dpp v237, v101 row_shr:1 row_mask:0xf bank_mask:0xf
	v_pk_fma_f32 v[114:115], v[160:161], v[114:115], v[182:183]
	v_pk_fma_f32 v[116:117], v[162:163], v[116:117], v[184:185]
	v_pk_fma_f32 v[118:119], v[164:165], v[118:119], v[186:187]
	v_pk_fma_f32 v[120:121], v[166:167], v[120:121], v[188:189]
	v_pk_fma_f32 v[114:115], v[152:153], v[106:107], v[114:115]
	v_pk_fma_f32 v[116:117], v[154:155], v[108:109], v[116:117]
	v_pk_fma_f32 v[118:119], v[156:157], v[98:99], v[118:119]
	v_pk_fma_f32 v[120:121], v[158:159], v[100:101], v[120:121]
	v_pk_fma_f32 v[114:115], v[144:145], v[110:111], v[114:115]
	v_pk_fma_f32 v[116:117], v[146:147], v[112:113], v[116:117]
	v_pk_fma_f32 v[118:119], v[148:149], v[102:103], v[118:119]
	v_pk_fma_f32 v[120:121], v[150:151], v[104:105], v[120:121]
	v_pk_fma_f32 v[106:107], v[160:161], v[106:107], v[182:183]
	v_pk_fma_f32 v[108:109], v[162:163], v[108:109], v[184:185]
	v_pk_fma_f32 v[98:99], v[164:165], v[98:99], v[186:187]
	v_pk_fma_f32 v[100:101], v[166:167], v[100:101], v[188:189]
	v_pk_fma_f32 v[106:107], v[152:153], v[110:111], v[106:107]
	v_pk_fma_f32 v[108:109], v[154:155], v[112:113], v[108:109]
	v_pk_fma_f32 v[98:99], v[156:157], v[102:103], v[98:99]
	v_pk_fma_f32 v[100:101], v[158:159], v[104:105], v[100:101]
	v_pk_fma_f32 v[106:107], v[144:145], v[126:127], v[106:107]
	v_pk_fma_f32 v[108:109], v[146:147], v[128:129], v[108:109]
	v_pk_fma_f32 v[98:99], v[148:149], v[122:123], v[98:99]
	v_pk_fma_f32 v[100:101], v[150:151], v[124:125], v[100:101]
	v_pk_fma_f32 v[110:111], v[160:161], v[110:111], v[182:183]
	v_pk_fma_f32 v[112:113], v[162:163], v[112:113], v[184:185]
	v_pk_fma_f32 v[102:103], v[164:165], v[102:103], v[186:187]
	v_pk_fma_f32 v[104:105], v[166:167], v[104:105], v[188:189]
	v_pk_fma_f32 v[110:111], v[152:153], v[126:127], v[110:111]
	v_pk_fma_f32 v[112:113], v[154:155], v[128:129], v[112:113]
	v_pk_fma_f32 v[102:103], v[156:157], v[122:123], v[102:103]
	v_pk_fma_f32 v[104:105], v[158:159], v[124:125], v[104:105]
	v_pk_fma_f32 v[110:111], v[144:145], v[230:231], v[110:111]
	v_pk_fma_f32 v[112:113], v[146:147], v[232:233], v[112:113]
	v_pk_fma_f32 v[102:103], v[148:149], v[238:239], v[102:103]
	v_pk_fma_f32 v[104:105], v[150:151], v[240:241], v[104:105]
	v_pk_fma_f32 v[126:127], v[160:161], v[126:127], v[182:183]
	v_pk_fma_f32 v[128:129], v[162:163], v[128:129], v[184:185]
	v_pk_fma_f32 v[122:123], v[164:165], v[122:123], v[186:187]
	v_pk_fma_f32 v[124:125], v[166:167], v[124:125], v[188:189]
	v_pk_fma_f32 v[126:127], v[152:153], v[230:231], v[126:127]
	v_pk_fma_f32 v[128:129], v[154:155], v[232:233], v[128:129]
	v_pk_fma_f32 v[122:123], v[156:157], v[238:239], v[122:123]
	v_pk_fma_f32 v[124:125], v[158:159], v[240:241], v[124:125]
	v_pk_fma_f32 v[126:127], v[144:145], v[226:227], v[126:127]
	v_pk_fma_f32 v[128:129], v[146:147], v[228:229], v[128:129]
	v_pk_fma_f32 v[122:123], v[148:149], v[234:235], v[122:123]
	v_pk_fma_f32 v[124:125], v[150:151], v[236:237], v[124:125]
	v_pk_mul_f32 v[226:227], v[126:127], s[80:81]
	v_pk_mul_f32 v[228:229], v[128:129], s[80:81]
	v_pk_mul_f32 v[230:231], v[110:111], s[80:81]
	v_pk_mul_f32 v[232:233], v[112:113], s[80:81]
	v_pk_mul_f32 v[234:235], v[106:107], s[80:81]
	v_pk_mul_f32 v[236:237], v[108:109], s[80:81]
	v_pk_mul_f32 v[238:239], v[114:115], s[80:81]
	v_pk_mul_f32 v[240:241], v[116:117], s[80:81]
	v_exp_f32_e32 v226, v226
	v_exp_f32_e32 v227, v227
	v_exp_f32_e32 v228, v228
	v_exp_f32_e32 v229, v229
	v_exp_f32_e32 v230, v230
	v_exp_f32_e32 v231, v231
	v_exp_f32_e32 v232, v232
	v_exp_f32_e32 v233, v233
	v_exp_f32_e32 v234, v234
	v_exp_f32_e32 v235, v235
	v_exp_f32_e32 v236, v236
	v_exp_f32_e32 v237, v237
	v_exp_f32_e32 v238, v238
	v_exp_f32_e32 v239, v239
	v_exp_f32_e32 v240, v240
	v_exp_f32_e32 v241, v241
	v_pk_add_f32 v[226:227], v[226:227], s[24:25]
	v_pk_add_f32 v[228:229], v[228:229], s[24:25]
	v_pk_add_f32 v[230:231], v[230:231], s[24:25]
	v_pk_add_f32 v[232:233], v[232:233], s[24:25]
	v_pk_add_f32 v[234:235], v[234:235], s[24:25]
	v_pk_add_f32 v[236:237], v[236:237], s[24:25]
	v_pk_add_f32 v[238:239], v[238:239], s[24:25]
	v_pk_add_f32 v[240:241], v[240:241], s[24:25]
	v_rcp_f32_e32 v226, v226
	v_rcp_f32_e32 v227, v227
	v_rcp_f32_e32 v228, v228
	v_rcp_f32_e32 v229, v229
	v_rcp_f32_e32 v230, v230
	v_rcp_f32_e32 v231, v231
	v_rcp_f32_e32 v232, v232
	v_rcp_f32_e32 v233, v233
	v_rcp_f32_e32 v234, v234
	v_rcp_f32_e32 v235, v235
	v_rcp_f32_e32 v236, v236
	v_rcp_f32_e32 v237, v237
	v_rcp_f32_e32 v238, v238
	v_rcp_f32_e32 v239, v239
	v_rcp_f32_e32 v240, v240
	v_rcp_f32_e32 v241, v241
	v_pk_mul_f32 v[126:127], v[126:127], v[226:227]
	v_pk_mul_f32 v[128:129], v[128:129], v[228:229]
	v_pk_mul_f32 v[110:111], v[110:111], v[230:231]
	v_pk_mul_f32 v[112:113], v[112:113], v[232:233]
	v_pk_mul_f32 v[106:107], v[106:107], v[234:235]
	v_pk_mul_f32 v[108:109], v[108:109], v[236:237]
	v_pk_mul_f32 v[114:115], v[114:115], v[238:239]
	v_pk_mul_f32 v[116:117], v[116:117], v[240:241]
	v_pk_mul_f32 v[126:127], v[126:127], v[122:123]
	v_pk_mul_f32 v[128:129], v[128:129], v[124:125]
	v_pk_mul_f32 v[110:111], v[110:111], v[102:103]
	v_pk_mul_f32 v[112:113], v[112:113], v[104:105]
	v_pk_mul_f32 v[106:107], v[106:107], v[98:99]
	v_pk_mul_f32 v[108:109], v[108:109], v[100:101]
	v_pk_mul_f32 v[114:115], v[114:115], v[118:119]
	v_pk_mul_f32 v[116:117], v[116:117], v[120:121]
	v_cvt_pk_bf16_f32 v122, v126, v127
	v_cvt_pk_bf16_f32 v123, v128, v129
	v_cvt_pk_bf16_f32 v102, v110, v111
	v_cvt_pk_bf16_f32 v103, v112, v113
	v_cvt_pk_bf16_f32 v98, v106, v107
	v_cvt_pk_bf16_f32 v99, v108, v109
	v_cvt_pk_bf16_f32 v118, v114, v115
	v_cvt_pk_bf16_f32 v119, v116, v117
	s_cmp_eq_u32 s100, 0
	s_cbranch_scc1 .Lue_z01
	ds_read_b128 v[226:229], v143 offset:16
	ds_read_b128 v[230:233], v143 offset:1040
	ds_read_b128 v[234:237], v143 offset:528
	ds_read_b128 v[238:241], v143 offset:1552
	s_branch .Lue_r01

; __device__ __forceinline__ unsigned cvt_pk_bf16(float lo, float hi) { unsigned r; asm volatile("v_cvt_pk_bf16_f32 %0, %1, %2" : "=v"(r) : "v"(lo), "v"(hi)); return r; }
; __device__ __forceinline__ float dpp_ror1(float s) { return __int_as_float(__builtin_amdgcn_mov_dpp(__float_as_int(s), 0x121, 0xf, 0xf, false)); }
; __device__ __forceinline__ float dpp_ror2(float s) { return __int_as_float(__builtin_amdgcn_mov_dpp(__float_as_int(s), 0x122, 0xf, 0xf, false)); }
; __device__ __forceinline__ float dpp_shr1(float old, float s) { return __int_as_float(__builtin_amdgcn_update_dpp(__float_as_int(old), __float_as_int(s), 0x111, 0xf, 0xf, false)); }
; __device__ __forceinline__ float dpp_shr2(float old, float s) { return __int_as_float(__builtin_amdgcn_update_dpp(__float_as_int(old), __float_as_int(s), 0x112, 0xf, 0xf, false)); }
;     __device__ __forceinline__ void operator()(const f32x4 (&acc_)[2][2][4][2], const Unit& u, int wr, int wc, int fr_, int fq_) const {
;     ...
;                 for (int m = 0; m < 4; ++m) {
;                     float o[4];
; #pragma unroll
;                     for (int e = 0; e < 4; ++e) {
;                         const float gc = acc[ai][0][m][n][e], gp = prev[0][e]; const float g1 = dpp_shr1(dpp_ror1(gp), gc), g2 = dpp_shr2(dpp_ror2(gp), gc);
;                         const float uc = acc[ai][1][m][n][e], up = prev[1][e]; const float u1 = dpp_shr1(dpp_ror1(up), uc), u2 = dpp_shr2(dpp_ror2(up), uc);
;                         const float gv = bia[0][e] + wgt[0][0][e] * g2 + wgt[1][0][e] * g1 + wgt[2][0][e] * gc;
;                         const float uv = bia[1][e] + wgt[0][1][e] * u2 + wgt[1][1][e] * u1 + wgt[2][1][e] * uc;
;                         o[e] = gv * __builtin_amdgcn_rcpf(1.0f + __builtin_amdgcn_exp2f(-1.4426950408889634f * gv)) * uv; }
;                     prev[0] = acc[ai][0][m][n]; prev[1] = acc[ai][1][m][n];
;                     const int row = u.pm * BM + ai * HALF + wr * 64 + m * 16 + fr;
;                     if (!(bi == 0 && m == 0 && fr < 2 && !seq0)) { u32x2 w; w.x = cvt_pk_bf16(o[0], o[1]); w.y = cvt_pk_bf16(o[2], o[3]); *(u32x2*)(act + (size_t)row * FF + ch0 + 4 * n) = w; }
.Lue_r01:
	s_waitcnt lgkmcnt(0)
	v_mov_b32_dpp v230, v50 row_shr:1 row_mask:0xf bank_mask:0xf
	v_mov_b32_dpp v231, v51 row_shr:1 row_mask:0xf bank_mask:0xf
	v_mov_b32_dpp v232, v52 row_shr:1 row_mask:0xf bank_mask:0xf
	v_mov_b32_dpp v233, v53 row_shr:1 row_mask:0xf bank_mask:0xf
	v_mov_b32_dpp v238, v54 row_shr:1 row_mask:0xf bank_mask:0xf
	v_mov_b32_dpp v239, v55 row_shr:1 row_mask:0xf bank_mask:0xf
	v_mov_b32_dpp v240, v56 row_shr:1 row_mask:0xf bank_mask:0xf
	v_mov_b32_dpp v241, v57 row_shr:1 row_mask:0xf bank_mask:0xf
	v_mov_b32_dpp v226, v42 row_shr:1 row_mask:0xf bank_mask:0xf
	v_mov_b32_dpp v227, v43 row_shr:1 row_mask:0xf bank_mask:0xf
	v_mov_b32_dpp v228, v44 row_shr:1 row_mask:0xf bank_mask:0xf
	v_mov_b32_dpp v229, v45 row_shr:1 row_mask:0xf bank_mask:0xf
	v_mov_b32_dpp v234, v34 row_shr:1 row_mask:0xf bank_mask:0xf
	v_mov_b32_dpp v235, v35 row_shr:1 row_mask:0xf bank_mask:0xf
	v_mov_b32_dpp v236, v36 row_shr:1 row_mask:0xf bank_mask:0xf
	v_mov_b32_dpp v237, v37 row_shr:1 row_mask:0xf bank_mask:0xf
	v_pk_fma_f32 v[50:51], v[206:207], v[50:51], v[218:219]
	v_pk_fma_f32 v[52:53], v[208:209], v[52:53], v[220:221]
	v_pk_fma_f32 v[54:55], v[210:211], v[54:55], v[222:223]
	v_pk_fma_f32 v[56:57], v[212:213], v[56:57], v[224:225]
	v_pk_fma_f32 v[50:51], v[198:199], v[42:43], v[50:51]
	v_pk_fma_f32 v[52:53], v[200:201], v[44:45], v[52:53]
	v_pk_fma_f32 v[54:55], v[202:203], v[34:35], v[54:55]
	v_pk_fma_f32 v[56:57], v[204:205], v[36:37], v[56:57]
	v_pk_fma_f32 v[50:51], v[190:191], v[46:47], v[50:51]
	v_pk_fma_f32 v[52:53], v[192:193], v[48:49], v[52:53]
	v_pk_fma_f32 v[54:55], v[194:195], v[38:39], v[54:55]
	v_pk_fma_f32 v[56:57], v[196:197], v[40:41], v[56:57]
	v_pk_fma_f32 v[42:43], v[206:207], v[42:43], v[218:219]
	v_pk_fma_f32 v[44:45], v[208:209], v[44:45], v[220:221]
	v_pk_fma_f32 v[34:35], v[210:211], v[34:35], v[222:223]
	v_pk_fma_f32 v[36:37], v[212:213], v[36:37], v[224:225]
	v_pk_fma_f32 v[42:43], v[198:199], v[46:47], v[42:43]
	v_pk_fma_f32 v[44:45], v[200:201], v[48:49], v[44:45]
	v_pk_fma_f32 v[34:35], v[202:203], v[38:39], v[34:35]
	v_pk_fma_f32 v[36:37], v[204:205], v[40:41], v[36:37]
	v_pk_fma_f32 v[42:43], v[190:191], v[82:83], v[42:43]
	v_pk_fma_f32 v[44:45], v[192:193], v[84:85], v[44:45]
	v_pk_fma_f32 v[34:35], v[194:195], v[78:79], v[34:35]
	v_pk_fma_f32 v[36:37], v[196:197], v[80:81], v[36:37]
	v_pk_fma_f32 v[46:47], v[206:207], v[46:47], v[218:219]
	v_pk_fma_f32 v[48:49], v[208:209], v[48:49], v[220:221]
	v_pk_fma_f32 v[38:39], v[210:211], v[38:39], v[222:223]
	v_pk_fma_f32 v[40:41], v[212:213], v[40:41], v[224:225]
	v_pk_fma_f32 v[46:47], v[198:199], v[82:83], v[46:47]
	v_pk_fma_f32 v[48:49], v[200:201], v[84:85], v[48:49]
	v_pk_fma_f32 v[38:39], v[202:203], v[78:79], v[38:39]
	v_pk_fma_f32 v[40:41], v[204:205], v[80:81], v[40:41]
	v_pk_fma_f32 v[46:47], v[190:191], v[230:231], v[46:47]
	v_pk_fma_f32 v[48:49], v[192:193], v[232:233], v[48:49]
	v_pk_fma_f32 v[38:39], v[194:195], v[238:239], v[38:39]
	v_pk_fma_f32 v[40:41], v[196:197], v[240:241], v[40:41]
	v_pk_fma_f32 v[82:83], v[206:207], v[82:83], v[218:219]
	v_pk_fma_f32 v[84:85], v[208:209], v[84:85], v[220:221]
	v_pk_fma_f32 v[78:79], v[210:211], v[78:79], v[222:223]
	v_pk_fma_f32 v[80:81], v[212:213], v[80:81], v[224:225]
	v_pk_fma_f32 v[82:83], v[198:199], v[230:231], v[82:83]
	v_pk_fma_f32 v[84:85], v[200:201], v[232:233], v[84:85]
	v_pk_fma_f32 v[78:79], v[202:203], v[238:239], v[78:79]
	v_pk_fma_f32 v[80:81], v[204:205], v[240:241], v[80:81]
	v_pk_fma_f32 v[82:83], v[190:191], v[226:227], v[82:83]
	v_pk_fma_f32 v[84:85], v[192:193], v[228:229], v[84:85]
	v_pk_fma_f32 v[78:79], v[194:195], v[234:235], v[78:79]
	v_pk_fma_f32 v[80:81], v[196:197], v[236:237], v[80:81]
	v_pk_mul_f32 v[226:227], v[82:83], s[80:81]
	v_pk_mul_f32 v[228:229], v[84:85], s[80:81]
	v_pk_mul_f32 v[230:231], v[46:47], s[80:81]
	v_pk_mul_f32 v[232:233], v[48:49], s[80:81]
	v_pk_mul_f32 v[234:235], v[42:43], s[80:81]
	v_pk_mul_f32 v[236:237], v[44:45], s[80:81]
	v_pk_mul_f32 v[238:239], v[50:51], s[80:81]
	v_pk_mul_f32 v[240:241], v[52:53], s[80:81]
	v_exp_f32_e32 v226, v226
	v_exp_f32_e32 v227, v227
	v_exp_f32_e32 v228, v228
	v_exp_f32_e32 v229, v229
	v_exp_f32_e32 v230, v230
	v_exp_f32_e32 v231, v231
	v_exp_f32_e32 v232, v232
	v_exp_f32_e32 v233, v233
	v_exp_f32_e32 v234, v234
	v_exp_f32_e32 v235, v235
	v_exp_f32_e32 v236, v236
	v_exp_f32_e32 v237, v237
	v_exp_f32_e32 v238, v238
	v_exp_f32_e32 v239, v239
	v_exp_f32_e32 v240, v240
	v_exp_f32_e32 v241, v241
	v_pk_add_f32 v[226:227], v[226:227], s[24:25]
	v_pk_add_f32 v[228:229], v[228:229], s[24:25]
	v_pk_add_f32 v[230:231], v[230:231], s[24:25]
	v_pk_add_f32 v[232:233], v[232:233], s[24:25]
	v_pk_add_f32 v[234:235], v[234:235], s[24:25]
	v_pk_add_f32 v[236:237], v[236:237], s[24:25]
	v_pk_add_f32 v[238:239], v[238:239], s[24:25]
	v_pk_add_f32 v[240:241], v[240:241], s[24:25]
	v_rcp_f32_e32 v226, v226
	v_rcp_f32_e32 v227, v227
	v_rcp_f32_e32 v228, v228
	v_rcp_f32_e32 v229, v229
	v_rcp_f32_e32 v230, v230
	v_rcp_f32_e32 v231, v231
	v_rcp_f32_e32 v232, v232
	v_rcp_f32_e32 v233, v233
	v_rcp_f32_e32 v234, v234
	v_rcp_f32_e32 v235, v235
	v_rcp_f32_e32 v236, v236
	v_rcp_f32_e32 v237, v237
	v_rcp_f32_e32 v238, v238
	v_rcp_f32_e32 v239, v239
	v_rcp_f32_e32 v240, v240
	v_rcp_f32_e32 v241, v241
	v_pk_mul_f32 v[82:83], v[82:83], v[226:227]
	v_pk_mul_f32 v[84:85], v[84:85], v[228:229]
	v_pk_mul_f32 v[46:47], v[46:47], v[230:231]
	v_pk_mul_f32 v[48:49], v[48:49], v[232:233]
	v_pk_mul_f32 v[42:43], v[42:43], v[234:235]
	v_pk_mul_f32 v[44:45], v[44:45], v[236:237]
	v_pk_mul_f32 v[50:51], v[50:51], v[238:239]
	v_pk_mul_f32 v[52:53], v[52:53], v[240:241]
	v_pk_mul_f32 v[82:83], v[82:83], v[78:79]
	v_pk_mul_f32 v[84:85], v[84:85], v[80:81]
	v_pk_mul_f32 v[46:47], v[46:47], v[38:39]
	v_pk_mul_f32 v[48:49], v[48:49], v[40:41]
	v_pk_mul_f32 v[42:43], v[42:43], v[34:35]
	v_pk_mul_f32 v[44:45], v[44:45], v[36:37]
	v_pk_mul_f32 v[50:51], v[50:51], v[54:55]
	v_pk_mul_f32 v[52:53], v[52:53], v[56:57]
	v_cvt_pk_bf16_f32 v124, v82, v83
	v_cvt_pk_bf16_f32 v125, v84, v85
	v_cvt_pk_bf16_f32 v104, v46, v47
	v_cvt_pk_bf16_f32 v105, v48, v49
	v_cvt_pk_bf16_f32 v100, v42, v43
	v_cvt_pk_bf16_f32 v101, v44, v45
	v_cvt_pk_bf16_f32 v120, v50, v51
	v_cvt_pk_bf16_f32 v121, v52, v53
	s_add_u32 s6, s8, 0x0
	s_addc_u32 s7, s9, 0
	s_andn2_b64 exec, exec, s[76:77]
	global_store_dwordx4 v140, v[122:125], s[6:7]
	s_mov_b64 exec, -1
	s_add_u32 s6, s8, 0x2c00
	s_addc_u32 s7, s9, 0
	s_andn2_b64 exec, exec, s[76:77]
	global_store_dwordx4 v140, v[102:105], s[6:7]
	s_mov_b64 exec, -1
	s_add_u32 s6, s8, 0x5800
	s_addc_u32 s7, s9, 0
	global_store_dwordx4 v140, v[98:101], s[6:7]
	s_add_u32 s6, s8, 0x8400
	s_addc_u32 s7, s9, 0
	global_store_dwordx4 v140, v[118:121], s[6:7]
	ds_read_b128 v[226:229], v143 offset:4096
	ds_read_b128 v[230:233], v143 offset:5120
	ds_read_b128 v[234:237], v143 offset:4608
	ds_read_b128 v[238:241], v143 offset:5632
	s_waitcnt lgkmcnt(0)
; #define PG8_LAS __attribute__((address_space(3)))
; __device__ __forceinline__ unsigned cvt_pk_bf16(float lo, float hi) { unsigned r; asm volatile("v_cvt_pk_bf16_f32 %0, %1, %2" : "=v"(r) : "v"(lo), "v"(hi)); return r; }
; __device__ __forceinline__ float dpp_ror1(float s) { return __int_as_float(__builtin_amdgcn_mov_dpp(__float_as_int(s), 0x121, 0xf, 0xf, false)); }
; __device__ __forceinline__ float dpp_ror2(float s) { return __int_as_float(__builtin_amdgcn_mov_dpp(__float_as_int(s), 0x122, 0xf, 0xf, false)); }
;     __device__ __forceinline__ void operator()(const f32x4 (&acc_)[2][2][4][2], const Unit& u, int wr, int wc, int fr_, int fq_) const {
;     ...
;             for (int ai = 0; ai < 2; ++ai) {
;                 const int bi = 2 * ai + wr;
;                 f32x4 prev[2];
; #pragma unroll
;                 for (int bj = 0; bj < 2; ++bj) { const f32x4 v = *(const PG8_LAS f32x4*)(xch + ((bi > 0 ? bi - 1 : 0) * 2 + (fr & 1)) * 256 + bj * 128 + chl + 4 * n);
;                     prev[bj] = bi > 0 ? v : (f32x4){0.f, 0.f, 0.f, 0.f}; }
; #pragma unroll
;                 for (int m = 0; m < 4; ++m) {
;                     float o[4];
; #pragma unroll
;                     for (int e = 0; e < 4; ++e) {
;                         const float gc = acc[ai][0][m][n][e], gp = prev[0][e]; const float g1 = dpp_shr1(dpp_ror1(gp), gc), g2 = dpp_shr2(dpp_ror2(gp), gc);
;                         const float uc = acc[ai][1][m][n][e], up = prev[1][e]; const float u1 = dpp_shr1(dpp_ror1(up), uc), u2 = dpp_shr2(dpp_ror2(up), uc);
;                         const float gv = bia[0][e] + wgt[0][0][e] * g2 + wgt[1][0][e] * g1 + wgt[2][0][e] * gc;
;                         const float uv = bia[1][e] + wgt[0][1][e] * u2 + wgt[1][1][e] * u1 + wgt[2][1][e] * uc;
;                         o[e] = gv * __builtin_amdgcn_rcpf(1.0f + __builtin_amdgcn_exp2f(-1.4426950408889634f * gv)) * uv; }
;                     prev[0] = acc[ai][0][m][n]; prev[1] = acc[ai][1][m][n];
;                     const int row = u.pm * BM + ai * HALF + wr * 64 + m * 16 + fr;
;                     if (!(bi == 0 && m == 0 && fr < 2 && !seq0)) { u32x2 w; w.x = cvt_pk_bf16(o[0], o[1]); w.y = cvt_pk_bf16(o[2], o[3]); *(u32x2*)(act + (size_t)row * FF + ch0 + 4 * n) = w; }
	v_mov_b32_dpp v230, v90 row_shr:1 row_mask:0xf bank_mask:0xf
	v_mov_b32_dpp v231, v91 row_shr:1 row_mask:0xf bank_mask:0xf
	v_mov_b32_dpp v232, v92 row_shr:1 row_mask:0xf bank_mask:0xf
	v_mov_b32_dpp v233, v93 row_shr:1 row_mask:0xf bank_mask:0xf
	v_mov_b32_dpp v238, v94 row_shr:1 row_mask:0xf bank_mask:0xf
	v_mov_b32_dpp v239, v95 row_shr:1 row_mask:0xf bank_mask:0xf
	v_mov_b32_dpp v240, v96 row_shr:1 row_mask:0xf bank_mask:0xf
	v_mov_b32_dpp v241, v97 row_shr:1 row_mask:0xf bank_mask:0xf
	v_mov_b32_dpp v226, v66 row_shr:1 row_mask:0xf bank_mask:0xf
	v_mov_b32_dpp v227, v67 row_shr:1 row_mask:0xf bank_mask:0xf
	v_mov_b32_dpp v228, v68 row_shr:1 row_mask:0xf bank_mask:0xf
	v_mov_b32_dpp v229, v69 row_shr:1 row_mask:0xf bank_mask:0xf
	v_mov_b32_dpp v234, v58 row_shr:1 row_mask:0xf bank_mask:0xf
	v_mov_b32_dpp v235, v59 row_shr:1 row_mask:0xf bank_mask:0xf
	v_mov_b32_dpp v236, v60 row_shr:1 row_mask:0xf bank_mask:0xf
	v_mov_b32_dpp v237, v61 row_shr:1 row_mask:0xf bank_mask:0xf
	v_pk_fma_f32 v[90:91], v[160:161], v[90:91], v[182:183]
	v_pk_fma_f32 v[92:93], v[162:163], v[92:93], v[184:185]
	v_pk_fma_f32 v[94:95], v[164:165], v[94:95], v[186:187]
	v_pk_fma_f32 v[96:97], v[166:167], v[96:97], v[188:189]
	v_pk_fma_f32 v[90:91], v[152:153], v[66:67], v[90:91]
	v_pk_fma_f32 v[92:93], v[154:155], v[68:69], v[92:93]
	v_pk_fma_f32 v[94:95], v[156:157], v[58:59], v[94:95]
	v_pk_fma_f32 v[96:97], v[158:159], v[60:61], v[96:97]
	v_pk_fma_f32 v[90:91], v[144:145], v[70:71], v[90:91]
	v_pk_fma_f32 v[92:93], v[146:147], v[72:73], v[92:93]
	v_pk_fma_f32 v[94:95], v[148:149], v[62:63], v[94:95]
	v_pk_fma_f32 v[96:97], v[150:151], v[64:65], v[96:97]
	v_pk_fma_f32 v[66:67], v[160:161], v[66:67], v[182:183]
	v_pk_fma_f32 v[68:69], v[162:163], v[68:69], v[184:185]
	v_pk_fma_f32 v[58:59], v[164:165], v[58:59], v[186:187]
	v_pk_fma_f32 v[60:61], v[166:167], v[60:61], v[188:189]
	v_pk_fma_f32 v[66:67], v[152:153], v[70:71], v[66:67]
	v_pk_fma_f32 v[68:69], v[154:155], v[72:73], v[68:69]
	v_pk_fma_f32 v[58:59], v[156:157], v[62:63], v[58:59]
	v_pk_fma_f32 v[60:61], v[158:159], v[64:65], v[60:61]
	v_pk_fma_f32 v[66:67], v[144:145], v[86:87], v[66:67]
	v_pk_fma_f32 v[68:69], v[146:147], v[88:89], v[68:69]
	v_pk_fma_f32 v[58:59], v[148:149], v[74:75], v[58:59]
	v_pk_fma_f32 v[60:61], v[150:151], v[76:77], v[60:61]
	v_pk_fma_f32 v[70:71], v[160:161], v[70:71], v[182:183]
	v_pk_fma_f32 v[72:73], v[162:163], v[72:73], v[184:185]
	v_pk_fma_f32 v[62:63], v[164:165], v[62:63], v[186:187]
	v_pk_fma_f32 v[64:65], v[166:167], v[64:65], v[188:189]
	v_pk_fma_f32 v[70:71], v[152:153], v[86:87], v[70:71]
	v_pk_fma_f32 v[72:73], v[154:155], v[88:89], v[72:73]
	v_pk_fma_f32 v[62:63], v[156:157], v[74:75], v[62:63]
	v_pk_fma_f32 v[64:65], v[158:159], v[76:77], v[64:65]
	v_pk_fma_f32 v[70:71], v[144:145], v[230:231], v[70:71]
	v_pk_fma_f32 v[72:73], v[146:147], v[232:233], v[72:73]
	v_pk_fma_f32 v[62:63], v[148:149], v[238:239], v[62:63]
	v_pk_fma_f32 v[64:65], v[150:151], v[240:241], v[64:65]
	v_pk_fma_f32 v[86:87], v[160:161], v[86:87], v[182:183]
	v_pk_fma_f32 v[88:89], v[162:163], v[88:89], v[184:185]
	v_pk_fma_f32 v[74:75], v[164:165], v[74:75], v[186:187]
	v_pk_fma_f32 v[76:77], v[166:167], v[76:77], v[188:189]
	v_pk_fma_f32 v[86:87], v[152:153], v[230:231], v[86:87]
	v_pk_fma_f32 v[88:89], v[154:155], v[232:233], v[88:89]
	v_pk_fma_f32 v[74:75], v[156:157], v[238:239], v[74:75]
	v_pk_fma_f32 v[76:77], v[158:159], v[240:241], v[76:77]
	v_pk_fma_f32 v[86:87], v[144:145], v[226:227], v[86:87]
	v_pk_fma_f32 v[88:89], v[146:147], v[228:229], v[88:89]
	v_pk_fma_f32 v[74:75], v[148:149], v[234:235], v[74:75]
	v_pk_fma_f32 v[76:77], v[150:151], v[236:237], v[76:77]
	v_pk_mul_f32 v[226:227], v[86:87], s[80:81]
	v_pk_mul_f32 v[228:229], v[88:89], s[80:81]
	v_pk_mul_f32 v[230:231], v[70:71], s[80:81]
	v_pk_mul_f32 v[232:233], v[72:73], s[80:81]
	v_pk_mul_f32 v[234:235], v[66:67], s[80:81]
	v_pk_mul_f32 v[236:237], v[68:69], s[80:81]
	v_pk_mul_f32 v[238:239], v[90:91], s[80:81]
	v_pk_mul_f32 v[240:241], v[92:93], s[80:81]
	v_exp_f32_e32 v226, v226
	v_exp_f32_e32 v227, v227
	v_exp_f32_e32 v228, v228
	v_exp_f32_e32 v229, v229
	v_exp_f32_e32 v230, v230
	v_exp_f32_e32 v231, v231
	v_exp_f32_e32 v232, v232
	v_exp_f32_e32 v233, v233
	v_exp_f32_e32 v234, v234
	v_exp_f32_e32 v235, v235
	v_exp_f32_e32 v236, v236
	v_exp_f32_e32 v237, v237
	v_exp_f32_e32 v238, v238
	v_exp_f32_e32 v239, v239
	v_exp_f32_e32 v240, v240
	v_exp_f32_e32 v241, v241
	v_pk_add_f32 v[226:227], v[226:227], s[24:25]
	v_pk_add_f32 v[228:229], v[228:229], s[24:25]
	v_pk_add_f32 v[230:231], v[230:231], s[24:25]
	v_pk_add_f32 v[232:233], v[232:233], s[24:25]
	v_pk_add_f32 v[234:235], v[234:235], s[24:25]
	v_pk_add_f32 v[236:237], v[236:237], s[24:25]
	v_pk_add_f32 v[238:239], v[238:239], s[24:25]
	v_pk_add_f32 v[240:241], v[240:241], s[24:25]
	v_rcp_f32_e32 v226, v226
	v_rcp_f32_e32 v227, v227
	v_rcp_f32_e32 v228, v228
	v_rcp_f32_e32 v229, v229
	v_rcp_f32_e32 v230, v230
	v_rcp_f32_e32 v231, v231
	v_rcp_f32_e32 v232, v232
	v_rcp_f32_e32 v233, v233
	v_rcp_f32_e32 v234, v234
	v_rcp_f32_e32 v235, v235
	v_rcp_f32_e32 v236, v236
	v_rcp_f32_e32 v237, v237
	v_rcp_f32_e32 v238, v238
	v_rcp_f32_e32 v239, v239
	v_rcp_f32_e32 v240, v240
	v_rcp_f32_e32 v241, v241
	v_pk_mul_f32 v[86:87], v[86:87], v[226:227]
	v_pk_mul_f32 v[88:89], v[88:89], v[228:229]
	v_pk_mul_f32 v[70:71], v[70:71], v[230:231]
	v_pk_mul_f32 v[72:73], v[72:73], v[232:233]
	v_pk_mul_f32 v[66:67], v[66:67], v[234:235]
	v_pk_mul_f32 v[68:69], v[68:69], v[236:237]
	v_pk_mul_f32 v[90:91], v[90:91], v[238:239]
	v_pk_mul_f32 v[92:93], v[92:93], v[240:241]
	v_pk_mul_f32 v[86:87], v[86:87], v[74:75]
	v_pk_mul_f32 v[88:89], v[88:89], v[76:77]
	v_pk_mul_f32 v[70:71], v[70:71], v[62:63]
	v_pk_mul_f32 v[72:73], v[72:73], v[64:65]
	v_pk_mul_f32 v[66:67], v[66:67], v[58:59]
	v_pk_mul_f32 v[68:69], v[68:69], v[60:61]
	v_pk_mul_f32 v[90:91], v[90:91], v[94:95]
	v_pk_mul_f32 v[92:93], v[92:93], v[96:97]
	v_cvt_pk_bf16_f32 v74, v86, v87
	v_cvt_pk_bf16_f32 v75, v88, v89
	v_cvt_pk_bf16_f32 v62, v70, v71
	v_cvt_pk_bf16_f32 v63, v72, v73
	v_cvt_pk_bf16_f32 v58, v66, v67
	v_cvt_pk_bf16_f32 v59, v68, v69
	v_cvt_pk_bf16_f32 v94, v90, v91
	v_cvt_pk_bf16_f32 v95, v92, v93
	ds_read_b128 v[226:229], v143 offset:4112
	ds_read_b128 v[230:233], v143 offset:5136
	ds_read_b128 v[234:237], v143 offset:4624
	ds_read_b128 v[238:241], v143 offset:5648
	s_waitcnt lgkmcnt(0)
; __device__ __forceinline__ unsigned cvt_pk_bf16(float lo, float hi) { unsigned r; asm volatile("v_cvt_pk_bf16_f32 %0, %1, %2" : "=v"(r) : "v"(lo), "v"(hi)); return r; }
; __device__ __forceinline__ float dpp_ror1(float s) { return __int_as_float(__builtin_amdgcn_mov_dpp(__float_as_int(s), 0x121, 0xf, 0xf, false)); }
; __device__ __forceinline__ float dpp_ror2(float s) { return __int_as_float(__builtin_amdgcn_mov_dpp(__float_as_int(s), 0x122, 0xf, 0xf, false)); }
; __device__ __forceinline__ float dpp_shr1(float old, float s) { return __int_as_float(__builtin_amdgcn_update_dpp(__float_as_int(old), __float_as_int(s), 0x111, 0xf, 0xf, false)); }
; __device__ __forceinline__ float dpp_shr2(float old, float s) { return __int_as_float(__builtin_amdgcn_update_dpp(__float_as_int(old), __float_as_int(s), 0x112, 0xf, 0xf, false)); }
;     __device__ __forceinline__ void operator()(const f32x4 (&acc_)[2][2][4][2], const Unit& u, int wr, int wc, int fr_, int fq_) const {
;     ...
;                 for (int m = 0; m < 4; ++m) {
;                     float o[4];
; #pragma unroll
;                     for (int e = 0; e < 4; ++e) {
;                         const float gc = acc[ai][0][m][n][e], gp = prev[0][e]; const float g1 = dpp_shr1(dpp_ror1(gp), gc), g2 = dpp_shr2(dpp_ror2(gp), gc);
;                         const float uc = acc[ai][1][m][n][e], up = prev[1][e]; const float u1 = dpp_shr1(dpp_ror1(up), uc), u2 = dpp_shr2(dpp_ror2(up), uc);
;                         const float gv = bia[0][e] + wgt[0][0][e] * g2 + wgt[1][0][e] * g1 + wgt[2][0][e] * gc;
;                         const float uv = bia[1][e] + wgt[0][1][e] * u2 + wgt[1][1][e] * u1 + wgt[2][1][e] * uc;
;                         o[e] = gv * __builtin_amdgcn_rcpf(1.0f + __builtin_amdgcn_exp2f(-1.4426950408889634f * gv)) * uv; }
;                     prev[0] = acc[ai][0][m][n]; prev[1] = acc[ai][1][m][n];
;                     const int row = u.pm * BM + ai * HALF + wr * 64 + m * 16 + fr;
;                     if (!(bi == 0 && m == 0 && fr < 2 && !seq0)) { u32x2 w; w.x = cvt_pk_bf16(o[0], o[1]); w.y = cvt_pk_bf16(o[2], o[3]); *(u32x2*)(act + (size_t)row * FF + ch0 + 4 * n) = w; }
	v_mov_b32_dpp v230, v26 row_shr:1 row_mask:0xf bank_mask:0xf
	v_mov_b32_dpp v231, v27 row_shr:1 row_mask:0xf bank_mask:0xf
	v_mov_b32_dpp v232, v28 row_shr:1 row_mask:0xf bank_mask:0xf
	v_mov_b32_dpp v233, v29 row_shr:1 row_mask:0xf bank_mask:0xf
	v_mov_b32_dpp v238, v30 row_shr:1 row_mask:0xf bank_mask:0xf
	v_mov_b32_dpp v239, v31 row_shr:1 row_mask:0xf bank_mask:0xf
	v_mov_b32_dpp v240, v32 row_shr:1 row_mask:0xf bank_mask:0xf
	v_mov_b32_dpp v241, v33 row_shr:1 row_mask:0xf bank_mask:0xf
	v_mov_b32_dpp v226, v8 row_shr:1 row_mask:0xf bank_mask:0xf
	v_mov_b32_dpp v227, v9 row_shr:1 row_mask:0xf bank_mask:0xf
	v_mov_b32_dpp v228, v10 row_shr:1 row_mask:0xf bank_mask:0xf
	v_mov_b32_dpp v229, v11 row_shr:1 row_mask:0xf bank_mask:0xf
	v_mov_b32_dpp v234, v0 row_shr:1 row_mask:0xf bank_mask:0xf
	v_mov_b32_dpp v235, v1 row_shr:1 row_mask:0xf bank_mask:0xf
	v_mov_b32_dpp v236, v2 row_shr:1 row_mask:0xf bank_mask:0xf
	v_mov_b32_dpp v237, v3 row_shr:1 row_mask:0xf bank_mask:0xf
	v_pk_fma_f32 v[26:27], v[206:207], v[26:27], v[218:219]
	v_pk_fma_f32 v[28:29], v[208:209], v[28:29], v[220:221]
	v_pk_fma_f32 v[30:31], v[210:211], v[30:31], v[222:223]
	v_pk_fma_f32 v[32:33], v[212:213], v[32:33], v[224:225]
	v_pk_fma_f32 v[26:27], v[198:199], v[8:9], v[26:27]
	v_pk_fma_f32 v[28:29], v[200:201], v[10:11], v[28:29]
	v_pk_fma_f32 v[30:31], v[202:203], v[0:1], v[30:31]
	v_pk_fma_f32 v[32:33], v[204:205], v[2:3], v[32:33]
	v_pk_fma_f32 v[26:27], v[190:191], v[12:13], v[26:27]
	v_pk_fma_f32 v[28:29], v[192:193], v[14:15], v[28:29]
	v_pk_fma_f32 v[30:31], v[194:195], v[4:5], v[30:31]
	v_pk_fma_f32 v[32:33], v[196:197], v[6:7], v[32:33]
	v_pk_fma_f32 v[8:9], v[206:207], v[8:9], v[218:219]
	v_pk_fma_f32 v[10:11], v[208:209], v[10:11], v[220:221]
	v_pk_fma_f32 v[0:1], v[210:211], v[0:1], v[222:223]
	v_pk_fma_f32 v[2:3], v[212:213], v[2:3], v[224:225]
	v_pk_fma_f32 v[8:9], v[198:199], v[12:13], v[8:9]
	v_pk_fma_f32 v[10:11], v[200:201], v[14:15], v[10:11]
	v_pk_fma_f32 v[0:1], v[202:203], v[4:5], v[0:1]
	v_pk_fma_f32 v[2:3], v[204:205], v[6:7], v[2:3]
	v_pk_fma_f32 v[8:9], v[190:191], v[22:23], v[8:9]
	v_pk_fma_f32 v[10:11], v[192:193], v[24:25], v[10:11]
	v_pk_fma_f32 v[0:1], v[194:195], v[16:17], v[0:1]
	v_pk_fma_f32 v[2:3], v[196:197], v[18:19], v[2:3]
	v_pk_fma_f32 v[12:13], v[206:207], v[12:13], v[218:219]
	v_pk_fma_f32 v[14:15], v[208:209], v[14:15], v[220:221]
	v_pk_fma_f32 v[4:5], v[210:211], v[4:5], v[222:223]
	v_pk_fma_f32 v[6:7], v[212:213], v[6:7], v[224:225]
	v_pk_fma_f32 v[12:13], v[198:199], v[22:23], v[12:13]
	v_pk_fma_f32 v[14:15], v[200:201], v[24:25], v[14:15]
	v_pk_fma_f32 v[4:5], v[202:203], v[16:17], v[4:5]
	v_pk_fma_f32 v[6:7], v[204:205], v[18:19], v[6:7]
	v_pk_fma_f32 v[12:13], v[190:191], v[230:231], v[12:13]
	v_pk_fma_f32 v[14:15], v[192:193], v[232:233], v[14:15]
	v_pk_fma_f32 v[4:5], v[194:195], v[238:239], v[4:5]
	v_pk_fma_f32 v[6:7], v[196:197], v[240:241], v[6:7]
	v_pk_fma_f32 v[22:23], v[206:207], v[22:23], v[218:219]
	v_pk_fma_f32 v[24:25], v[208:209], v[24:25], v[220:221]
	v_pk_fma_f32 v[16:17], v[210:211], v[16:17], v[222:223]
	v_pk_fma_f32 v[18:19], v[212:213], v[18:19], v[224:225]
	v_pk_fma_f32 v[22:23], v[198:199], v[230:231], v[22:23]
	v_pk_fma_f32 v[24:25], v[200:201], v[232:233], v[24:25]
	v_pk_fma_f32 v[16:17], v[202:203], v[238:239], v[16:17]
	v_pk_fma_f32 v[18:19], v[204:205], v[240:241], v[18:19]
	v_pk_fma_f32 v[22:23], v[190:191], v[226:227], v[22:23]
	v_pk_fma_f32 v[24:25], v[192:193], v[228:229], v[24:25]
	v_pk_fma_f32 v[16:17], v[194:195], v[234:235], v[16:17]
	v_pk_fma_f32 v[18:19], v[196:197], v[236:237], v[18:19]
	v_pk_mul_f32 v[226:227], v[22:23], s[80:81]
	v_pk_mul_f32 v[228:229], v[24:25], s[80:81]
	v_pk_mul_f32 v[230:231], v[12:13], s[80:81]
	v_pk_mul_f32 v[232:233], v[14:15], s[80:81]
	v_pk_mul_f32 v[234:235], v[8:9], s[80:81]
	v_pk_mul_f32 v[236:237], v[10:11], s[80:81]
	v_pk_mul_f32 v[238:239], v[26:27], s[80:81]
	v_pk_mul_f32 v[240:241], v[28:29], s[80:81]
	v_exp_f32_e32 v226, v226
	v_exp_f32_e32 v227, v227
	v_exp_f32_e32 v228, v228
	v_exp_f32_e32 v229, v229
	v_exp_f32_e32 v230, v230
	v_exp_f32_e32 v231, v231
	v_exp_f32_e32 v232, v232
	v_exp_f32_e32 v233, v233
	v_exp_f32_e32 v234, v234
	v_exp_f32_e32 v235, v235
	v_exp_f32_e32 v236, v236
	v_exp_f32_e32 v237, v237
	v_exp_f32_e32 v238, v238
	v_exp_f32_e32 v239, v239
	v_exp_f32_e32 v240, v240
	v_exp_f32_e32 v241, v241
	v_pk_add_f32 v[226:227], v[226:227], s[24:25]
	v_pk_add_f32 v[228:229], v[228:229], s[24:25]
	v_pk_add_f32 v[230:231], v[230:231], s[24:25]
	v_pk_add_f32 v[232:233], v[232:233], s[24:25]
	v_pk_add_f32 v[234:235], v[234:235], s[24:25]
	v_pk_add_f32 v[236:237], v[236:237], s[24:25]
	v_pk_add_f32 v[238:239], v[238:239], s[24:25]
	v_pk_add_f32 v[240:241], v[240:241], s[24:25]
	v_rcp_f32_e32 v226, v226
	v_rcp_f32_e32 v227, v227
	v_rcp_f32_e32 v228, v228
	v_rcp_f32_e32 v229, v229
	v_rcp_f32_e32 v230, v230
	v_rcp_f32_e32 v231, v231
	v_rcp_f32_e32 v232, v232
	v_rcp_f32_e32 v233, v233
	v_rcp_f32_e32 v234, v234
	v_rcp_f32_e32 v235, v235
	v_rcp_f32_e32 v236, v236
	v_rcp_f32_e32 v237, v237
	v_rcp_f32_e32 v238, v238
	v_rcp_f32_e32 v239, v239
	v_rcp_f32_e32 v240, v240
	v_rcp_f32_e32 v241, v241
	v_pk_mul_f32 v[22:23], v[22:23], v[226:227]
	v_pk_mul_f32 v[24:25], v[24:25], v[228:229]
	v_pk_mul_f32 v[12:13], v[12:13], v[230:231]
	v_pk_mul_f32 v[14:15], v[14:15], v[232:233]
	v_pk_mul_f32 v[8:9], v[8:9], v[234:235]
	v_pk_mul_f32 v[10:11], v[10:11], v[236:237]
	v_pk_mul_f32 v[26:27], v[26:27], v[238:239]
	v_pk_mul_f32 v[28:29], v[28:29], v[240:241]
	v_pk_mul_f32 v[22:23], v[22:23], v[16:17]
	v_pk_mul_f32 v[24:25], v[24:25], v[18:19]
	v_pk_mul_f32 v[12:13], v[12:13], v[4:5]
	v_pk_mul_f32 v[14:15], v[14:15], v[6:7]
	v_pk_mul_f32 v[8:9], v[8:9], v[0:1]
	v_pk_mul_f32 v[10:11], v[10:11], v[2:3]
	v_pk_mul_f32 v[26:27], v[26:27], v[30:31]
	v_pk_mul_f32 v[28:29], v[28:29], v[32:33]
	v_cvt_pk_bf16_f32 v76, v22, v23
	v_cvt_pk_bf16_f32 v77, v24, v25
	v_cvt_pk_bf16_f32 v64, v12, v13
	v_cvt_pk_bf16_f32 v65, v14, v15
	v_cvt_pk_bf16_f32 v60, v8, v9
	v_cvt_pk_bf16_f32 v61, v10, v11
	v_cvt_pk_bf16_f32 v96, v26, v27
	v_cvt_pk_bf16_f32 v97, v28, v29
	s_add_u32 s6, s8, 0x160000
	s_addc_u32 s7, s9, 0
	global_store_dwordx4 v140, v[74:77], s[6:7]
	s_add_u32 s6, s8, 0x162c00
	s_addc_u32 s7, s9, 0
	global_store_dwordx4 v140, v[62:65], s[6:7]
	s_add_u32 s6, s8, 0x165800
	s_addc_u32 s7, s9, 0
	global_store_dwordx4 v140, v[58:61], s[6:7]
	s_add_u32 s6, s8, 0x168400
	s_addc_u32 s7, s9, 0
	global_store_dwordx4 v140, v[94:97], s[6:7]
	s_andn2_b64 vcc, exec, s[4:5]
	s_mov_b64 s[4:5], -1
	s_cbranch_vccnz .LBB0_712
	s_andn2_b64 vcc, exec, s[50:51]
	s_cbranch_vccnz .LBB0_711
	s_barrier
	s_branch .LBB0_711

; #define LAS __attribute__((address_space(3)))
; __global__ void __launch_bounds__(NWAVES * 64, 2) fwd_mega(Args args_unused) {
;     extern __shared__ __attribute__((aligned(16))) unsigned char lds_raw[];
;     cg::grid_group grid = cg::this_grid();
;     LAS unsigned char* lds = (LAS unsigned char*)lds_raw;
;     const int wave_s = __builtin_amdgcn_readfirstlane(threadIdx.x >> 6);
;     volatile LAS unsigned* bar_st = (volatile LAS unsigned*)(lds + 131072);
;     if (threadIdx.x < 2) bar_st[threadIdx.x] = 0u;
;     __syncthreads();
;     { const Args* ap0 = (const Args*)__builtin_amdgcn_kernarg_segment_ptr(); (void)xcd_barrier_post((unsigned*)(ap0->ws + WS_CTL), bar_st); }
; #pragma nounroll
	.amdhsa_kernel _Z8fwd_mega4Args
		.amdhsa_group_segment_fixed_size 0
		.amdhsa_private_segment_fixed_size 0
		.amdhsa_kernarg_size 400
		.amdhsa_user_sgpr_count 2
		.amdhsa_user_sgpr_dispatch_ptr 0
		.amdhsa_user_sgpr_queue_ptr 0
		.amdhsa_user_sgpr_kernarg_segment_ptr 1
		.amdhsa_user_sgpr_dispatch_id 0
		.amdhsa_user_sgpr_kernarg_preload_length 0
		.amdhsa_user_sgpr_kernarg_preload_offset 0
		.amdhsa_user_sgpr_private_segment_size 0
		.amdhsa_uses_dynamic_stack 0
		.amdhsa_enable_private_segment 0
		.amdhsa_system_sgpr_workgroup_id_x 1
		.amdhsa_system_sgpr_workgroup_id_y 0
		.amdhsa_system_sgpr_workgroup_id_z 0
		.amdhsa_system_sgpr_workgroup_info 0
		.amdhsa_system_vgpr_workitem_id 2
		.amdhsa_next_free_vgpr 256
		.amdhsa_next_free_sgpr 102
		.amdhsa_accum_offset 256
		.amdhsa_reserve_vcc 1
		.amdhsa_float_round_mode_32 0
		.amdhsa_float_round_mode_16_64 0
		.amdhsa_float_denorm_mode_32 3
		.amdhsa_float_denorm_mode_16_64 3
		.amdhsa_dx10_clamp 1
		.amdhsa_ieee_mode 1
		.amdhsa_fp16_overflow 0
		.amdhsa_tg_split 0
		.amdhsa_exception_fp_ieee_invalid_op 0
		.amdhsa_exception_fp_denorm_src 0
		.amdhsa_exception_fp_ieee_div_zero 0
		.amdhsa_exception_fp_ieee_overflow 0
		.amdhsa_exception_fp_ieee_underflow 0
		.amdhsa_exception_fp_ieee_inexact 0
		.amdhsa_exception_int_div_zero 0
	.end_amdhsa_kernel

; #define LAS __attribute__((address_space(3)))
; __global__ void __launch_bounds__(NWAVES * 64, 2) fwd_mega(Args args_unused) {
;     extern __shared__ __attribute__((aligned(16))) unsigned char lds_raw[];
;     cg::grid_group grid = cg::this_grid();
;     LAS unsigned char* lds = (LAS unsigned char*)lds_raw;
;     const int wave_s = __builtin_amdgcn_readfirstlane(threadIdx.x >> 6);
amdhsa.kernels:
  - .agpr_count:     0
    .args:
      - .offset:         0
        .size:           144
        .value_kind:     by_value
      - .offset:         144
        .size:           4
        .value_kind:     hidden_block_count_x
      - .offset:         148
        .size:           4
        .value_kind:     hidden_block_count_y
      - .offset:         152
        .size:           4
        .value_kind:     hidden_block_count_z
      - .offset:         156
        .size:           2
        .value_kind:     hidden_group_size_x
      - .offset:         158
        .size:           2
        .value_kind:     hidden_group_size_y
      - .offset:         160
        .size:           2
        .value_kind:     hidden_group_size_z
      - .offset:         162
        .size:           2
        .value_kind:     hidden_remainder_x
      - .offset:         164
        .size:           2
        .value_kind:     hidden_remainder_y
      - .offset:         166
        .size:           2
        .value_kind:     hidden_remainder_z
      - .offset:         184
        .size:           8
        .value_kind:     hidden_global_offset_x
      - .offset:         192
        .size:           8
        .value_kind:     hidden_global_offset_y
      - .offset:         200
        .size:           8
        .value_kind:     hidden_global_offset_z
      - .offset:         208
        .size:           2
        .value_kind:     hidden_grid_dims
      - .offset:         232
        .size:           8
        .value_kind:     hidden_multigrid_sync_arg
      - .offset:         264
        .size:           4
        .value_kind:     hidden_dynamic_lds_size
    .group_segment_fixed_size: 0
    .kernarg_segment_align: 8
    .kernarg_segment_size: 400
    .language:       OpenCL C
    .language_version:
      - 2
      - 0
    .max_flat_workgroup_size: 512
    .name:           _Z8fwd_mega4Args
    .private_segment_fixed_size: 0
    .sgpr_count:     108
    .sgpr_spill_count: 8
    .symbol:         _Z8fwd_mega4Args.kd
    .uniform_work_group_size: 1
    .uses_dynamic_stack: false
    .vgpr_count:     256
    .vgpr_spill_count: 0
    .wavefront_size: 64
